# speedup vs baseline: 1.0089x; 1.0020x over previous
.Lxl_spin_1:
	s_add_u32 s98, s98, 1
	s_cmp_lt_u32 s98, 0x40000
	s_cbranch_scc0 .Lxl_exit_1
	s_nop 0
	global_load_dword v3, v2, s[4:5] sc1
	s_waitcnt vmcnt(0)
	v_cmp_gt_u32_e32 vcc, s100, v3
	s_cbranch_vccnz .Lxl_spin_1
